# GEMM K-loop: per-phase s_setprio flips replaced by one static s_setprio 1 for the trailing wave half (wr=1), on top of the attention store transposition
# speedup vs baseline: 1.0248x; 1.0083x over previous
; #define PG8_STAGE(bufoff, gbase, voff) do { _Pragma("unroll") for (int _i = 0; _i < 2; ++_i) \
;         __builtin_amdgcn_global_load_lds((const unsigned*)((const char*)(gbase) + (voff)[_i]), (PG8_LAS unsigned*)(lds + (bufoff) + ldsw + _i * 8192), 16, 0, 0); } while (0)
; #define PG8_LDA(dst, b, h) do { _Pragma("unroll") for (int m = 0; m < 4; ++m) _Pragma("unroll") for (int k = 0; k < 2; ++k) dst[m][k] = *(const PG8_LAS bf16x8*)(lds + PG8_SA(b, h) + aoff + m * 2048 + k * 1024); } while (0)
; #define PG8_LDB(dst, b, h) do { _Pragma("unroll") for (int n = 0; n < 2; ++n) _Pragma("unroll") for (int k = 0; k < 2; ++k) dst[n][k] = *(const PG8_LAS bf16x8*)(lds + PG8_SB(b, h) + boff + n * 2048 + k * 1024); } while (0)
; #define PG8_WAIT_V(n) asm volatile("s_waitcnt vmcnt(" #n ")" ::: "memory")
; #define PG8_WAIT_L(n) asm volatile("s_waitcnt lgkmcnt(" #n ")" ::: "memory")
; template <class Epi, class Sched, bool ALIGN_EPI = false, bool SP2 = false>
; __device__ __forceinline__ void gemm_phase(PG8_LAS unsigned char* lds, const Gemm g, const Sched& S, const Epi& E, const int tid_in) {
;     ...
;         const bool has_next = S.next(ui + 1, nxt);
;         const char* nA = has_next ? (const char*)g.A + (size_t)nxt.pm * tstep : cA; const char* nB = has_next ? (const char*)g.Bt + (size_t)nxt.pn * tstep : cB;
;         for (int t = 0; t < nt; t += 2) {
;             if (t == E.mid_t) E.mid(acc, cur, wr, wc, fr, fq);
;             const bool last = (t == nt - 2);
;             const char* a1 = cA + (size_t)(t + 1) * kstep;
;             const char* a2 = last ? nA : cA + (size_t)(t + 2) * kstep; const char* b2 = last ? nB : cB + (size_t)(t + 2) * kstep;
;             const char* a3 = a2 + kstep; const char* b3 = b2 + kstep;
;             if (last && has_next) S.a_ready(nxt);
;             if constexpr (SP2) {
;             PG8_LDB(B0, 0, 0); PG8_LDB(B1, 0, 1); PG8_SCHED; PG8_LDA(At, 0, 0); PG8_STAGE(PG8_SA(1, 1), a1 + hstep, voffA);
;             PG8_WAIT_V(8); PG8_WAIT_L(0); PG8_BAR; PG8_MMA(0, 0, At, B0); PG8_MMA(0, 1, At, B1); PG8_BAR; PG8_SCHED;
;     ...
; #pragma unroll
;         for (int a = 0; a < 2; ++a)
; #pragma unroll
;             for (int b = 0; b < 2; ++b)
; #pragma unroll
;                 for (int m = 0; m < 4; ++m)
; #pragma unroll
;                     for (int n = 0; n < 2; ++n) acc[a][b][m][n] = (f32x4){0.f, 0.f, 0.f, 0.f};
.LBB0_138:
	v_lshl_add_u32 v232, s48, 8, v221
	s_add_u32 s48, s46, 0x100
	s_addc_u32 s49, s47, 0
	s_add_u32 s0, s44, 0x80
	s_addc_u32 s1, s45, 0
	v_mov_b32_e32 v2, 0
	v_lshl_or_b32 v233, s55, 8, v229
	v_lshl_add_u64 v[208:209], s[0:1], 0, v[204:205]
	v_lshl_add_u64 v[210:211], s[0:1], 0, v[206:207]
	s_and_b64 vcc, exec, s[20:21]
	s_cbranch_vccnz .Lnoprio
	s_setprio 1
.Lnoprio:
	s_mov_b32 s46, 0
	s_mov_b64 s[0:1], 0
	v_mov_b32_e32 v3, v2
	v_mov_b32_e32 v4, v2
	v_mov_b32_e32 v5, v2
	v_mov_b32_e32 v6, v2
	v_mov_b32_e32 v7, v2
	v_mov_b32_e32 v8, v2
	v_mov_b32_e32 v9, v2
	v_mov_b32_e32 v18, v2
	v_mov_b32_e32 v19, v2
	v_mov_b32_e32 v20, v2
	v_mov_b32_e32 v21, v2
	v_mov_b32_e32 v22, v2
	v_mov_b32_e32 v23, v2
	v_mov_b32_e32 v24, v2
	v_mov_b32_e32 v25, v2
	v_mov_b32_e32 v34, v2
	v_mov_b32_e32 v35, v2
	v_mov_b32_e32 v36, v2
	v_mov_b32_e32 v37, v2
	v_mov_b32_e32 v38, v2
	v_mov_b32_e32 v39, v2
	v_mov_b32_e32 v40, v2
	v_mov_b32_e32 v41, v2
	v_mov_b32_e32 v50, v2
	v_mov_b32_e32 v51, v2
	v_mov_b32_e32 v52, v2
	v_mov_b32_e32 v53, v2
	v_mov_b32_e32 v54, v2
	v_mov_b32_e32 v55, v2
	v_mov_b32_e32 v56, v2
	v_mov_b32_e32 v57, v2
	v_mov_b32_e32 v10, v2
	v_mov_b32_e32 v11, v2
	v_mov_b32_e32 v12, v2
	v_mov_b32_e32 v13, v2
	v_mov_b32_e32 v14, v2
	v_mov_b32_e32 v15, v2
	v_mov_b32_e32 v16, v2
	v_mov_b32_e32 v17, v2
	v_mov_b32_e32 v26, v2
	v_mov_b32_e32 v27, v2
	v_mov_b32_e32 v28, v2
	v_mov_b32_e32 v29, v2
	v_mov_b32_e32 v30, v2
	v_mov_b32_e32 v31, v2
	v_mov_b32_e32 v32, v2
	v_mov_b32_e32 v33, v2
	v_mov_b32_e32 v42, v2
	v_mov_b32_e32 v43, v2
	v_mov_b32_e32 v44, v2
	v_mov_b32_e32 v45, v2
	v_mov_b32_e32 v46, v2
	v_mov_b32_e32 v47, v2
	v_mov_b32_e32 v48, v2
	v_mov_b32_e32 v49, v2
	v_mov_b32_e32 v58, v2
	v_mov_b32_e32 v59, v2
	v_mov_b32_e32 v60, v2
	v_mov_b32_e32 v61, v2
	v_mov_b32_e32 v62, v2
	v_mov_b32_e32 v63, v2
	v_mov_b32_e32 v64, v2
	v_mov_b32_e32 v65, v2
	v_mov_b32_e32 v66, v2
	v_mov_b32_e32 v67, v2
	v_mov_b32_e32 v68, v2
	v_mov_b32_e32 v69, v2
	v_mov_b32_e32 v70, v2
	v_mov_b32_e32 v71, v2
	v_mov_b32_e32 v72, v2
	v_mov_b32_e32 v73, v2
	v_mov_b32_e32 v82, v2
	v_mov_b32_e32 v83, v2
	v_mov_b32_e32 v84, v2
	v_mov_b32_e32 v85, v2
	v_mov_b32_e32 v86, v2
	v_mov_b32_e32 v87, v2
	v_mov_b32_e32 v88, v2
	v_mov_b32_e32 v89, v2
	v_mov_b32_e32 v98, v2
	v_mov_b32_e32 v99, v2
	v_mov_b32_e32 v100, v2
	v_mov_b32_e32 v101, v2
	v_mov_b32_e32 v102, v2
	v_mov_b32_e32 v103, v2
	v_mov_b32_e32 v104, v2
	v_mov_b32_e32 v105, v2
	v_mov_b32_e32 v114, v2
	v_mov_b32_e32 v115, v2
	v_mov_b32_e32 v116, v2
	v_mov_b32_e32 v117, v2
	v_mov_b32_e32 v118, v2
	v_mov_b32_e32 v119, v2
	v_mov_b32_e32 v120, v2
	v_mov_b32_e32 v121, v2
	v_mov_b32_e32 v74, v2
	v_mov_b32_e32 v75, v2
	v_mov_b32_e32 v76, v2
	v_mov_b32_e32 v77, v2
	v_mov_b32_e32 v78, v2
	v_mov_b32_e32 v79, v2
	v_mov_b32_e32 v80, v2
	v_mov_b32_e32 v81, v2
	v_mov_b32_e32 v90, v2
	v_mov_b32_e32 v91, v2
	v_mov_b32_e32 v92, v2
	v_mov_b32_e32 v93, v2
	v_mov_b32_e32 v94, v2
	v_mov_b32_e32 v95, v2
	v_mov_b32_e32 v96, v2
	v_mov_b32_e32 v97, v2
	v_mov_b32_e32 v106, v2
	v_mov_b32_e32 v107, v2
	v_mov_b32_e32 v108, v2
	v_mov_b32_e32 v109, v2
	v_mov_b32_e32 v110, v2
	v_mov_b32_e32 v111, v2
	v_mov_b32_e32 v112, v2
	v_mov_b32_e32 v113, v2
	v_mov_b32_e32 v122, v2
	v_mov_b32_e32 v123, v2
	v_mov_b32_e32 v124, v2
	v_mov_b32_e32 v125, v2
	v_mov_b32_e32 v126, v2
	v_mov_b32_e32 v127, v2
	v_mov_b32_e32 v128, v2
	v_mov_b32_e32 v129, v2
	s_branch .LBB0_140
.LBB0_139:
	s_add_i32 s50, s46, 2
	s_add_u32 s47, s44, s0
	s_addc_u32 s51, s45, s1
	s_add_u32 s52, s47, 0x100
	s_addc_u32 s47, s51, 0
	s_add_u32 s51, s48, s0
	s_addc_u32 s53, s49, s1
	s_add_i32 s73, 0, 0x10000
	s_cmp_eq_u32 s67, s46
	s_cselect_b32 s47, s23, s47
	s_cselect_b32 s46, s22, s52
	v_add_u32_e32 v0, s73, v222
	s_cselect_b32 s53, s43, s53
	s_cselect_b32 s52, s42, s51
	s_add_i32 s51, 0, 0x14000
	ds_read_b128 v[130:133], v0
	ds_read_b128 v[134:137], v0 offset:1024
	ds_read_b128 v[138:141], v0 offset:2048
	ds_read_b128 v[142:145], v0 offset:3072
	v_add_u32_e32 v0, s51, v222
	ds_read_b128 v[146:149], v0
	ds_read_b128 v[150:153], v0 offset:1024
	ds_read_b128 v[154:157], v0 offset:2048
	ds_read_b128 v[158:161], v0 offset:3072
	v_lshl_add_u64 v[234:235], v[208:209], 0, s[0:1]
	s_add_i32 m0, s58, 0xc000
	ds_read_b128 v[162:165], v231
	ds_read_b128 v[166:169], v231 offset:1024
	ds_read_b128 v[170:173], v231 offset:2048
	ds_read_b128 v[174:177], v231 offset:3072
	ds_read_b128 v[178:181], v231 offset:4096
	ds_read_b128 v[182:185], v231 offset:5120
	ds_read_b128 v[186:189], v231 offset:6144
	ds_read_b128 v[190:193], v231 offset:7168
	global_load_lds_dwordx4 v[234:235], off
	v_lshl_add_u64 v[234:235], v[210:211], 0, s[0:1]
	s_add_i32 m0, s58, 0xe000
	s_nop 0
	global_load_lds_dwordx4 v[234:235], off
	s_waitcnt vmcnt(8)
	s_waitcnt lgkmcnt(0)
	s_barrier
; #define PG8_STAGE(bufoff, gbase, voff) do { _Pragma("unroll") for (int _i = 0; _i < 2; ++_i) \
;         __builtin_amdgcn_global_load_lds((const unsigned*)((const char*)(gbase) + (voff)[_i]), (PG8_LAS unsigned*)(lds + (bufoff) + ldsw + _i * 8192), 16, 0, 0); } while (0)
; #define PG8_LDA(dst, b, h) do { _Pragma("unroll") for (int m = 0; m < 4; ++m) _Pragma("unroll") for (int k = 0; k < 2; ++k) dst[m][k] = *(const PG8_LAS bf16x8*)(lds + PG8_SA(b, h) + aoff + m * 2048 + k * 1024); } while (0)
; #define PG8_MMA(ai, bj, At, Bt) do { __builtin_amdgcn_s_setprio(1); _Pragma("unroll") for (int m = 0; m < 4; ++m) _Pragma("unroll") for (int n = 0; n < 2; ++n) _Pragma("unroll") for (int k = 0; k < 2; ++k) \
;         acc[ai][bj][m][n] = __builtin_amdgcn_mfma_f32_16x16x32_bf16(Bt[n][k], At[m][k], acc[ai][bj][m][n], 0, 0, 0); __builtin_amdgcn_s_setprio(0); } while (0)
; #define PG8_WAIT_V(n) asm volatile("s_waitcnt vmcnt(" #n ")" ::: "memory")
; #define PG8_WAIT_L(n) asm volatile("s_waitcnt lgkmcnt(" #n ")" ::: "memory")
; #define PG8_BAR __builtin_amdgcn_s_barrier()
; #define PG8_SCHED __builtin_amdgcn_sched_barrier(0)
; template <class Epi, class Sched, bool ALIGN_EPI = false, bool SP2 = false>
; __device__ __forceinline__ void gemm_phase(PG8_LAS unsigned char* lds, const Gemm g, const Sched& S, const Epi& E, const int tid_in) {
;     ...
;             PG8_WAIT_V(8); PG8_WAIT_L(0); PG8_BAR; PG8_MMA(0, 0, At, B0); PG8_MMA(0, 1, At, B1); PG8_BAR; PG8_SCHED;
;             PG8_LDA(At, 0, 1); PG8_STAGE(PG8_SB(0, 0), b2, voffB); PG8_STAGE(PG8_SB(0, 1), b2 + hstep, voffB); PG8_STAGE(PG8_SA(0, 0), a2, voffA);
;             PG8_WAIT_V(8); PG8_WAIT_L(0); PG8_BAR; PG8_MMA(1, 0, At, B0); PG8_MMA(1, 1, At, B1); PG8_BAR; PG8_SCHED;
	s_waitcnt lgkmcnt(0)
	v_mfma_f32_16x16x32_bf16 v[126:129], v[130:133], v[162:165], v[126:129]
	v_mfma_f32_16x16x32_bf16 v[122:125], v[138:141], v[162:165], v[122:125]
	v_mfma_f32_16x16x32_bf16 v[110:113], v[130:133], v[170:173], v[110:113]
	v_mfma_f32_16x16x32_bf16 v[106:109], v[138:141], v[170:173], v[106:109]
	v_mfma_f32_16x16x32_bf16 v[94:97], v[130:133], v[178:181], v[94:97]
	v_mfma_f32_16x16x32_bf16 v[90:93], v[138:141], v[178:181], v[90:93]
	v_mfma_f32_16x16x32_bf16 v[78:81], v[130:133], v[186:189], v[78:81]
	v_mfma_f32_16x16x32_bf16 v[74:77], v[138:141], v[186:189], v[74:77]
	v_mfma_f32_16x16x32_bf16 v[126:129], v[134:137], v[166:169], v[126:129]
	v_mfma_f32_16x16x32_bf16 v[122:125], v[142:145], v[166:169], v[122:125]
	v_mfma_f32_16x16x32_bf16 v[110:113], v[134:137], v[174:177], v[110:113]
	v_mfma_f32_16x16x32_bf16 v[106:109], v[142:145], v[174:177], v[106:109]
	v_mfma_f32_16x16x32_bf16 v[94:97], v[134:137], v[182:185], v[94:97]
	v_mfma_f32_16x16x32_bf16 v[90:93], v[142:145], v[182:185], v[90:93]
	v_mfma_f32_16x16x32_bf16 v[78:81], v[134:137], v[190:193], v[78:81]
	v_mfma_f32_16x16x32_bf16 v[74:77], v[142:145], v[190:193], v[74:77]
	v_mfma_f32_16x16x32_bf16 v[118:121], v[146:149], v[162:165], v[118:121]
	v_mfma_f32_16x16x32_bf16 v[114:117], v[154:157], v[162:165], v[114:117]
	v_mfma_f32_16x16x32_bf16 v[102:105], v[146:149], v[170:173], v[102:105]
	v_mfma_f32_16x16x32_bf16 v[98:101], v[154:157], v[170:173], v[98:101]
	v_mfma_f32_16x16x32_bf16 v[86:89], v[146:149], v[178:181], v[86:89]
	v_mfma_f32_16x16x32_bf16 v[82:85], v[154:157], v[178:181], v[82:85]
	v_mfma_f32_16x16x32_bf16 v[70:73], v[146:149], v[186:189], v[70:73]
	v_mfma_f32_16x16x32_bf16 v[66:69], v[154:157], v[186:189], v[66:69]
	v_mfma_f32_16x16x32_bf16 v[118:121], v[150:153], v[166:169], v[118:121]
	v_mfma_f32_16x16x32_bf16 v[114:117], v[158:161], v[166:169], v[114:117]
	v_mfma_f32_16x16x32_bf16 v[102:105], v[150:153], v[174:177], v[102:105]
	v_mfma_f32_16x16x32_bf16 v[98:101], v[158:161], v[174:177], v[98:101]
	v_mfma_f32_16x16x32_bf16 v[86:89], v[150:153], v[182:185], v[86:89]
	v_mfma_f32_16x16x32_bf16 v[82:85], v[158:161], v[182:185], v[82:85]
	v_mfma_f32_16x16x32_bf16 v[70:73], v[150:153], v[190:193], v[70:73]
	v_mfma_f32_16x16x32_bf16 v[66:69], v[158:161], v[190:193], v[66:69]
	s_barrier
	s_add_i32 s73, s73, s57
	v_lshl_add_u64 v[234:235], s[52:53], 0, v[198:199]
	s_mov_b32 m0, s73
	ds_read_b128 v[162:165], v231 offset:16384
	ds_read_b128 v[166:169], v231 offset:17408
	ds_read_b128 v[170:173], v231 offset:18432
	ds_read_b128 v[174:177], v231 offset:19456
	ds_read_b128 v[178:181], v231 offset:20480
	ds_read_b128 v[182:185], v231 offset:21504
	ds_read_b128 v[186:189], v231 offset:22528
	ds_read_b128 v[190:193], v231 offset:23552
	global_load_lds_dwordx4 v[234:235], off
	s_add_i32 m0, s73, 0x2000
	v_lshl_add_u64 v[236:237], s[52:53], 0, v[202:203]
	s_add_u32 s52, s52, s34
	s_addc_u32 s53, s53, 0
	s_add_i32 s51, s51, s57
	global_load_lds_dwordx4 v[236:237], off
	v_lshl_add_u64 v[238:239], s[52:53], 0, v[198:199]
	s_mov_b32 m0, s51
	v_lshl_add_u64 v[240:241], s[52:53], 0, v[202:203]
	global_load_lds_dwordx4 v[238:239], off
	s_add_i32 m0, s51, 0x2000
	v_lshl_add_u64 v[242:243], s[46:47], 0, v[196:197]
	global_load_lds_dwordx4 v[240:241], off
	s_mov_b32 m0, s58
	v_lshl_add_u64 v[244:245], s[46:47], 0, v[200:201]
	global_load_lds_dwordx4 v[242:243], off
	s_mov_b32 m0, s59
	s_nop 0
	global_load_lds_dwordx4 v[244:245], off
	s_waitcnt vmcnt(8)
	s_waitcnt lgkmcnt(0)
	s_barrier
	s_waitcnt lgkmcnt(0)
	v_mfma_f32_16x16x32_bf16 v[62:65], v[130:133], v[162:165], v[62:65]
	v_mfma_f32_16x16x32_bf16 v[58:61], v[138:141], v[162:165], v[58:61]
	v_mfma_f32_16x16x32_bf16 v[46:49], v[130:133], v[170:173], v[46:49]
	v_mfma_f32_16x16x32_bf16 v[42:45], v[138:141], v[170:173], v[42:45]
	v_mfma_f32_16x16x32_bf16 v[30:33], v[130:133], v[178:181], v[30:33]
	v_mfma_f32_16x16x32_bf16 v[26:29], v[138:141], v[178:181], v[26:29]
	v_mfma_f32_16x16x32_bf16 v[14:17], v[130:133], v[186:189], v[14:17]
	v_mfma_f32_16x16x32_bf16 v[10:13], v[138:141], v[186:189], v[10:13]
	v_mfma_f32_16x16x32_bf16 v[62:65], v[134:137], v[166:169], v[62:65]
	v_mfma_f32_16x16x32_bf16 v[58:61], v[142:145], v[166:169], v[58:61]
	v_mfma_f32_16x16x32_bf16 v[46:49], v[134:137], v[174:177], v[46:49]
	v_mfma_f32_16x16x32_bf16 v[42:45], v[142:145], v[174:177], v[42:45]
	v_mfma_f32_16x16x32_bf16 v[30:33], v[134:137], v[182:185], v[30:33]
	v_mfma_f32_16x16x32_bf16 v[26:29], v[142:145], v[182:185], v[26:29]
	v_mfma_f32_16x16x32_bf16 v[14:17], v[134:137], v[190:193], v[14:17]
	v_mfma_f32_16x16x32_bf16 v[10:13], v[142:145], v[190:193], v[10:13]
	v_mfma_f32_16x16x32_bf16 v[54:57], v[146:149], v[162:165], v[54:57]
	v_mfma_f32_16x16x32_bf16 v[50:53], v[154:157], v[162:165], v[50:53]
	v_mfma_f32_16x16x32_bf16 v[38:41], v[146:149], v[170:173], v[38:41]
	v_mfma_f32_16x16x32_bf16 v[34:37], v[154:157], v[170:173], v[34:37]
	v_mfma_f32_16x16x32_bf16 v[22:25], v[146:149], v[178:181], v[22:25]
	v_mfma_f32_16x16x32_bf16 v[18:21], v[154:157], v[178:181], v[18:21]
	v_mfma_f32_16x16x32_bf16 v[6:9], v[146:149], v[186:189], v[6:9]
	v_mfma_f32_16x16x32_bf16 v[2:5], v[154:157], v[186:189], v[2:5]
	v_mfma_f32_16x16x32_bf16 v[54:57], v[150:153], v[166:169], v[54:57]
	v_mfma_f32_16x16x32_bf16 v[50:53], v[158:161], v[166:169], v[50:53]
	v_mfma_f32_16x16x32_bf16 v[38:41], v[150:153], v[174:177], v[38:41]
	v_mfma_f32_16x16x32_bf16 v[34:37], v[158:161], v[174:177], v[34:37]
	v_mfma_f32_16x16x32_bf16 v[22:25], v[150:153], v[182:185], v[22:25]
	v_mfma_f32_16x16x32_bf16 v[18:21], v[158:161], v[182:185], v[18:21]
	v_mfma_f32_16x16x32_bf16 v[6:9], v[150:153], v[190:193], v[6:9]
	v_mfma_f32_16x16x32_bf16 v[2:5], v[158:161], v[190:193], v[2:5]
	s_barrier
; #define PG8_STAGE(bufoff, gbase, voff) do { _Pragma("unroll") for (int _i = 0; _i < 2; ++_i) \
;         __builtin_amdgcn_global_load_lds((const unsigned*)((const char*)(gbase) + (voff)[_i]), (PG8_LAS unsigned*)(lds + (bufoff) + ldsw + _i * 8192), 16, 0, 0); } while (0)
; #define PG8_LDA(dst, b, h) do { _Pragma("unroll") for (int m = 0; m < 4; ++m) _Pragma("unroll") for (int k = 0; k < 2; ++k) dst[m][k] = *(const PG8_LAS bf16x8*)(lds + PG8_SA(b, h) + aoff + m * 2048 + k * 1024); } while (0)
; #define PG8_LDB(dst, b, h) do { _Pragma("unroll") for (int n = 0; n < 2; ++n) _Pragma("unroll") for (int k = 0; k < 2; ++k) dst[n][k] = *(const PG8_LAS bf16x8*)(lds + PG8_SB(b, h) + boff + n * 2048 + k * 1024); } while (0)
; #define PG8_MMA(ai, bj, At, Bt) do { __builtin_amdgcn_s_setprio(1); _Pragma("unroll") for (int m = 0; m < 4; ++m) _Pragma("unroll") for (int n = 0; n < 2; ++n) _Pragma("unroll") for (int k = 0; k < 2; ++k) \
;         acc[ai][bj][m][n] = __builtin_amdgcn_mfma_f32_16x16x32_bf16(Bt[n][k], At[m][k], acc[ai][bj][m][n], 0, 0, 0); __builtin_amdgcn_s_setprio(0); } while (0)
; #define PG8_WAIT_V(n) asm volatile("s_waitcnt vmcnt(" #n ")" ::: "memory")
; #define PG8_WAIT_L(n) asm volatile("s_waitcnt lgkmcnt(" #n ")" ::: "memory")
; #define PG8_BAR __builtin_amdgcn_s_barrier()
; #define PG8_SCHED __builtin_amdgcn_sched_barrier(0)
; template <class Epi, class Sched, bool ALIGN_EPI = false, bool SP2 = false>
; __device__ __forceinline__ void gemm_phase(PG8_LAS unsigned char* lds, const Gemm g, const Sched& S, const Epi& E, const int tid_in) {
;     ...
;             PG8_LDB(B0, 1, 0); PG8_LDB(B1, 1, 1); PG8_SCHED; PG8_LDA(At, 1, 0); PG8_STAGE(PG8_SA(0, 1), a2 + hstep, voffA);
;             PG8_WAIT_V(8); PG8_WAIT_L(0); PG8_BAR; PG8_MMA(0, 0, At, B0); PG8_MMA(0, 1, At, B1); PG8_BAR; PG8_SCHED;
;             PG8_LDA(At, 1, 1); PG8_STAGE(PG8_SB(1, 0), b3, voffB); PG8_STAGE(PG8_SB(1, 1), b3 + hstep, voffB); PG8_STAGE(PG8_SA(1, 0), a3, voffA);
;             PG8_WAIT_V(8); PG8_WAIT_L(0); PG8_BAR; PG8_MMA(1, 0, At, B0); PG8_MMA(1, 1, At, B1); PG8_BAR; PG8_SCHED;
	s_add_i32 s51, 0, 0x18000
	v_add_u32_e32 v0, s51, v222
	s_add_i32 s52, 0, 0x1c000
	ds_read_b128 v[130:133], v0
	ds_read_b128 v[134:137], v0 offset:1024
	ds_read_b128 v[138:141], v0 offset:2048
	ds_read_b128 v[142:145], v0 offset:3072
	v_add_u32_e32 v0, s52, v222
	ds_read_b128 v[146:149], v0
	ds_read_b128 v[150:153], v0 offset:1024
	ds_read_b128 v[154:157], v0 offset:2048
	ds_read_b128 v[158:161], v0 offset:3072
	s_add_u32 s46, s46, s34
	s_addc_u32 s47, s47, 0
	s_mov_b32 m0, s60
	v_lshl_add_u64 v[246:247], s[46:47], 0, v[196:197]
	ds_read_b128 v[162:165], v231 offset:32768
	ds_read_b128 v[166:169], v231 offset:33792
	ds_read_b128 v[170:173], v231 offset:34816
	ds_read_b128 v[174:177], v231 offset:35840
	ds_read_b128 v[178:181], v231 offset:36864
	ds_read_b128 v[182:185], v231 offset:37888
	ds_read_b128 v[186:189], v231 offset:38912
	ds_read_b128 v[190:193], v231 offset:39936
	global_load_lds_dwordx4 v[246:247], off
	v_lshl_add_u64 v[246:247], s[46:47], 0, v[200:201]
	s_mov_b32 m0, s61
	s_nop 0
	global_load_lds_dwordx4 v[246:247], off
	s_waitcnt vmcnt(8)
	s_waitcnt lgkmcnt(0)
	s_barrier
	s_waitcnt lgkmcnt(0)
	v_mfma_f32_16x16x32_bf16 v[126:129], v[130:133], v[162:165], v[126:129]
	v_mfma_f32_16x16x32_bf16 v[122:125], v[138:141], v[162:165], v[122:125]
	v_mfma_f32_16x16x32_bf16 v[110:113], v[130:133], v[170:173], v[110:113]
	v_mfma_f32_16x16x32_bf16 v[106:109], v[138:141], v[170:173], v[106:109]
	v_mfma_f32_16x16x32_bf16 v[94:97], v[130:133], v[178:181], v[94:97]
	v_mfma_f32_16x16x32_bf16 v[90:93], v[138:141], v[178:181], v[90:93]
	v_mfma_f32_16x16x32_bf16 v[78:81], v[130:133], v[186:189], v[78:81]
	v_mfma_f32_16x16x32_bf16 v[74:77], v[138:141], v[186:189], v[74:77]
	v_mfma_f32_16x16x32_bf16 v[126:129], v[134:137], v[166:169], v[126:129]
	v_mfma_f32_16x16x32_bf16 v[122:125], v[142:145], v[166:169], v[122:125]
	v_mfma_f32_16x16x32_bf16 v[110:113], v[134:137], v[174:177], v[110:113]
	v_mfma_f32_16x16x32_bf16 v[106:109], v[142:145], v[174:177], v[106:109]
	v_mfma_f32_16x16x32_bf16 v[94:97], v[134:137], v[182:185], v[94:97]
	v_mfma_f32_16x16x32_bf16 v[90:93], v[142:145], v[182:185], v[90:93]
	v_mfma_f32_16x16x32_bf16 v[78:81], v[134:137], v[190:193], v[78:81]
	v_mfma_f32_16x16x32_bf16 v[74:77], v[142:145], v[190:193], v[74:77]
	v_mfma_f32_16x16x32_bf16 v[118:121], v[146:149], v[162:165], v[118:121]
	v_mfma_f32_16x16x32_bf16 v[114:117], v[154:157], v[162:165], v[114:117]
	v_mfma_f32_16x16x32_bf16 v[102:105], v[146:149], v[170:173], v[102:105]
	v_mfma_f32_16x16x32_bf16 v[98:101], v[154:157], v[170:173], v[98:101]
	v_mfma_f32_16x16x32_bf16 v[86:89], v[146:149], v[178:181], v[86:89]
	v_mfma_f32_16x16x32_bf16 v[82:85], v[154:157], v[178:181], v[82:85]
	v_mfma_f32_16x16x32_bf16 v[70:73], v[146:149], v[186:189], v[70:73]
	v_mfma_f32_16x16x32_bf16 v[66:69], v[154:157], v[186:189], v[66:69]
	v_mfma_f32_16x16x32_bf16 v[118:121], v[150:153], v[166:169], v[118:121]
	v_mfma_f32_16x16x32_bf16 v[114:117], v[158:161], v[166:169], v[114:117]
	v_mfma_f32_16x16x32_bf16 v[102:105], v[150:153], v[174:177], v[102:105]
	v_mfma_f32_16x16x32_bf16 v[98:101], v[158:161], v[174:177], v[98:101]
	v_mfma_f32_16x16x32_bf16 v[86:89], v[150:153], v[182:185], v[86:89]
	v_mfma_f32_16x16x32_bf16 v[82:85], v[158:161], v[182:185], v[82:85]
	v_mfma_f32_16x16x32_bf16 v[70:73], v[150:153], v[190:193], v[70:73]
	v_mfma_f32_16x16x32_bf16 v[66:69], v[158:161], v[190:193], v[66:69]
	s_barrier
	s_add_i32 s46, s51, s57
	v_lshl_add_u64 v[234:235], v[234:235], 0, s[36:37]
	s_mov_b32 m0, s46
	ds_read_b128 v[162:165], v231 offset:49152
	ds_read_b128 v[166:169], v231 offset:50176
	ds_read_b128 v[170:173], v231 offset:51200
	ds_read_b128 v[174:177], v231 offset:52224
	ds_read_b128 v[178:181], v231 offset:53248
	ds_read_b128 v[182:185], v231 offset:54272
	ds_read_b128 v[186:189], v231 offset:55296
	ds_read_b128 v[190:193], v231 offset:56320
	global_load_lds_dwordx4 v[234:235], off
	v_lshl_add_u64 v[234:235], v[236:237], 0, s[36:37]
	s_add_i32 m0, s46, 0x2000
	s_add_i32 s46, s52, s57
	global_load_lds_dwordx4 v[234:235], off
	v_lshl_add_u64 v[234:235], v[238:239], 0, s[36:37]
	s_mov_b32 m0, s46
	s_nop 0
	global_load_lds_dwordx4 v[234:235], off
	v_lshl_add_u64 v[234:235], v[240:241], 0, s[36:37]
	s_add_i32 m0, s46, 0x2000
	s_nop 0
	global_load_lds_dwordx4 v[234:235], off
	v_lshl_add_u64 v[234:235], v[242:243], 0, s[36:37]
	s_mov_b32 m0, s65
	s_nop 0
	global_load_lds_dwordx4 v[234:235], off
	v_lshl_add_u64 v[234:235], v[244:245], 0, s[36:37]
	s_mov_b32 m0, s66
	s_nop 0
	global_load_lds_dwordx4 v[234:235], off
	s_waitcnt vmcnt(8)
	s_waitcnt lgkmcnt(0)
	s_barrier
	s_waitcnt lgkmcnt(0)
	v_mfma_f32_16x16x32_bf16 v[62:65], v[130:133], v[162:165], v[62:65]
	v_mfma_f32_16x16x32_bf16 v[58:61], v[138:141], v[162:165], v[58:61]
	v_mfma_f32_16x16x32_bf16 v[46:49], v[130:133], v[170:173], v[46:49]
	v_mfma_f32_16x16x32_bf16 v[42:45], v[138:141], v[170:173], v[42:45]
	v_mfma_f32_16x16x32_bf16 v[30:33], v[130:133], v[178:181], v[30:33]
	v_mfma_f32_16x16x32_bf16 v[26:29], v[138:141], v[178:181], v[26:29]
	v_mfma_f32_16x16x32_bf16 v[14:17], v[130:133], v[186:189], v[14:17]
	v_mfma_f32_16x16x32_bf16 v[10:13], v[138:141], v[186:189], v[10:13]
	v_mfma_f32_16x16x32_bf16 v[62:65], v[134:137], v[166:169], v[62:65]
	v_mfma_f32_16x16x32_bf16 v[58:61], v[142:145], v[166:169], v[58:61]
	v_mfma_f32_16x16x32_bf16 v[46:49], v[134:137], v[174:177], v[46:49]
	v_mfma_f32_16x16x32_bf16 v[42:45], v[142:145], v[174:177], v[42:45]
	v_mfma_f32_16x16x32_bf16 v[30:33], v[134:137], v[182:185], v[30:33]
	v_mfma_f32_16x16x32_bf16 v[26:29], v[142:145], v[182:185], v[26:29]
	v_mfma_f32_16x16x32_bf16 v[14:17], v[134:137], v[190:193], v[14:17]
	v_mfma_f32_16x16x32_bf16 v[10:13], v[142:145], v[190:193], v[10:13]
	v_mfma_f32_16x16x32_bf16 v[54:57], v[146:149], v[162:165], v[54:57]
	v_mfma_f32_16x16x32_bf16 v[50:53], v[154:157], v[162:165], v[50:53]
	v_mfma_f32_16x16x32_bf16 v[38:41], v[146:149], v[170:173], v[38:41]
	v_mfma_f32_16x16x32_bf16 v[34:37], v[154:157], v[170:173], v[34:37]
	v_mfma_f32_16x16x32_bf16 v[22:25], v[146:149], v[178:181], v[22:25]
	v_mfma_f32_16x16x32_bf16 v[18:21], v[154:157], v[178:181], v[18:21]
	v_mfma_f32_16x16x32_bf16 v[6:9], v[146:149], v[186:189], v[6:9]
	v_mfma_f32_16x16x32_bf16 v[2:5], v[154:157], v[186:189], v[2:5]
	v_mfma_f32_16x16x32_bf16 v[54:57], v[150:153], v[166:169], v[54:57]
	v_mfma_f32_16x16x32_bf16 v[50:53], v[158:161], v[166:169], v[50:53]
	v_mfma_f32_16x16x32_bf16 v[38:41], v[150:153], v[174:177], v[38:41]
	v_mfma_f32_16x16x32_bf16 v[34:37], v[158:161], v[174:177], v[34:37]
	v_mfma_f32_16x16x32_bf16 v[22:25], v[150:153], v[182:185], v[22:25]
	v_mfma_f32_16x16x32_bf16 v[18:21], v[158:161], v[182:185], v[18:21]
	v_mfma_f32_16x16x32_bf16 v[6:9], v[150:153], v[190:193], v[6:9]
	v_mfma_f32_16x16x32_bf16 v[2:5], v[158:161], v[190:193], v[2:5]
	s_barrier
	s_add_u32 s0, s0, 0x100
	s_addc_u32 s1, s1, 0
	s_cmp_ge_u32 s50, s63
	s_mov_b32 s46, s50
	s_cbranch_scc1 .LBB0_142

; #define PG8_BAR __builtin_amdgcn_s_barrier()
; template <class Epi, class Sched, bool ALIGN_EPI = false, bool SP2 = false>
; __device__ __forceinline__ void gemm_phase(PG8_LAS unsigned char* lds, const Gemm g, const Sched& S, const Epi& E, const int tid_in) {
;     ...
;         if constexpr (ALIGN_EPI) { if (wr == 0) PG8_BAR; }
;         if constexpr (!Epi::AFTER_DRAIN) { E(acc, cur, wr, wc, fr, fq); S.done(cur); }
;         if (!has_next) break;
.LBB0_142:
	s_setprio 0
	s_and_b64 vcc, exec, s[20:21]
	s_cbranch_vccz .LBB0_145
	s_barrier
	s_cmp_lt_i32 s9, 2
	s_mov_b64 s[0:1], -1
	s_cbranch_scc0 .LBB0_146
